# v53 + helper y-reduction LDS reads de-conflicted (XOR-swizzled read order per lane, same pairing, bit-identical)
# speedup vs baseline: 1.0141x; 1.0061x over previous
.LBB0_721:
	s_and_b64 s[8:9], s[0:1], exec
	v_readlane_b32 s8, v255, 9
	v_and_b32_e32 v166, 63, v44
	v_readlane_b32 s9, v255, 10
	v_and_b32_e32 v26, 31, v44
	v_lshlrev_b32_e32 v27, 6, v44
	s_cselect_b32 s27, s72, s9
	s_cselect_b32 s26, s39, s8
	s_mov_b64 s[8:9], -1
	s_cmp_lt_i32 s20, 4
	v_lshl_add_u32 v118, v45, 4, 0
	v_lshl_or_b32 v164, s42, 6, v166
	v_and_b32_e32 v119, 0x600, v27
	v_and_b32_e32 v123, 0x100, v27
	v_and_b32_e32 v129, 0xc0, v27
	v_lshlrev_b32_e32 v116, 2, v26
	s_waitcnt lgkmcnt(0)
	s_barrier
	s_cbranch_scc1 .LBB0_831
	v_lshl_or_b32 v167, s42, 2, v165
	s_mul_i32 s8, s42, 0x2100
	v_mov_b32_e32 v121, s7
	v_or_b32_e32 v120, s6, v46
	v_mad_u64_u32 v[124:125], s[6:7], v167, s69, v[118:119]
	s_add_i32 s8, s8, 0
	s_ashr_i32 s23, s22, 31
	v_lshlrev_b32_e32 v26, 2, v44
	v_lshrrev_b32_e32 v125, 5, v164
	s_add_i32 s15, s8, 0x1b000
	v_and_b32_e32 v122, 28, v26
	v_lshlrev_b32_e32 v26, 11, v125
	s_lshl_b64 s[42:43], s[22:23], 2
	v_add3_u32 v27, s70, v26, v119
	s_add_u32 s42, s26, s42
	v_add3_u32 v168, v27, v123, v129
	s_addc_u32 s43, s27, s43
	v_mov_b32_e32 v117, v115
	v_add_u32_e32 v27, 0x100, v164
	v_lshl_add_u64 v[126:127], s[42:43], 0, v[116:117]
	v_lshrrev_b32_e32 v117, 5, v27
	v_lshlrev_b32_e32 v27, 11, v117
	s_ashr_i32 s37, s36, 31
	v_add3_u32 v26, 0, v26, v119
	s_lshl_b64 s[36:37], s[36:37], 2
	v_add3_u32 v173, v26, v123, v129
	v_add3_u32 v26, 0, v27, v119
	s_add_u32 s36, s40, s36
	v_add3_u32 v174, v26, v123, v129
	v_lshlrev_b32_e32 v232, 2, v44
	v_and_b32_e32 v232, 48, v232
	v_xor_b32_e32 v233, 16, v232
	v_xor_b32_e32 v234, 32, v232
	v_xor_b32_e32 v235, 48, v232
	v_add_u32_e32 v224, v173, v232
	v_add_u32_e32 v225, v173, v233
	v_add_u32_e32 v226, v173, v234
	v_add_u32_e32 v227, v173, v235
	v_add_u32_e32 v228, 0x8000, v224
	v_add_u32_e32 v229, 0x8000, v225
	v_add_u32_e32 v230, 0x8000, v226
	v_add_u32_e32 v231, 0x8000, v227
	v_lshlrev_b32_e32 v26, 3, v44
	s_addc_u32 s37, s41, s37
	v_lshrrev_b32_e32 v171, 3, v166
	v_and_b32_e32 v128, 56, v26
	s_lshl_b64 s[40:41], s[22:23], 1
	v_add3_u32 v28, s70, v27, v119
	v_mul_u32_u24_e32 v26, 0x84, v128
	v_lshlrev_b32_e32 v27, 2, v171
	s_add_u32 s40, s16, s40
	v_lshl_add_u32 v176, v122, 2, s15
	v_add3_u32 v182, s15, v26, v27
	s_addc_u32 s41, s17, s41
	s_lshl_b32 s15, s20, 6
	v_or_b32_e32 v26, s15, v166
	s_addk_i32 s15, 0xff00
	v_add3_u32 v169, v28, v123, v129
	v_lshlrev_b32_e32 v28, 7, v167
	v_lshlrev_b32_e32 v114, 1, v122
	v_lshrrev_b32_e32 v183, 5, v26
	v_or_b32_e32 v26, s15, v166
	v_cmp_gt_u32_e64 s[6:7], 8, v45
	s_mov_b32 s45, 0
	v_cmp_eq_u32_e64 s[8:9], 0, v45
	v_add_u32_e32 v170, 64, v167
	v_add_u32_e32 v172, 0x50, v167
	v_add_u32_e32 v175, 0x60, v167
	v_add_u32_e32 v177, 0x70, v167
	v_mul_u32_u24_e32 v178, 0x84, v171
	v_or_b32_e32 v179, 8, v171
	v_or_b32_e32 v180, 16, v171
	v_or_b32_e32 v181, 24, v171
	v_lshl_add_u64 v[130:131], s[40:41], 0, v[114:115]
	v_lshrrev_b32_e32 v184, 5, v26
	v_lshl_or_b32 v185, s20, 2, v165
	s_mov_b32 s23, -4
	v_add_u32_e32 v186, v118, v28
	s_mov_b32 s49, s11
	s_mov_b32 s46, 0
	s_branch .LBB0_726

.LBB0_738:
	s_or_b64 exec, exec, s[40:41]
	ds_read_b128 v[106:109], v228 offset:45056
	ds_read_b128 v[110:113], v229 offset:45056
	ds_read_b128 v[10:13], v230 offset:45056
	ds_read_b128 v[14:17], v231 offset:45056
	v_sub_u32_e64 v114, s46, 1 clamp
	s_and_b64 vcc, exec, s[4:5]
	s_mov_b64 s[40:41], -1
	s_cbranch_vccnz .LBB0_740
	v_lshl_add_u32 v134, v114, 4, v125
	v_sub_u32_e32 v134, 0x1fff, v134
	s_mov_b64 s[40:41], 0

.LBB0_742:
	s_waitcnt lgkmcnt(2)
	v_pk_add_f32 v[108:109], v[108:109], v[112:113]
	v_pk_add_f32 v[106:107], v[106:107], v[110:111]
	s_waitcnt lgkmcnt(0)
	v_pk_add_f32 v[12:13], v[12:13], v[16:17]
	v_pk_add_f32 v[10:11], v[10:11], v[14:15]
	v_pk_add_f32 v[12:13], v[108:109], v[12:13]
	v_pk_add_f32 v[10:11], v[106:107], v[10:11]
	v_ashrrev_i32_e32 v135, 31, v134
	v_add_f32_e32 v10, v10, v11
	v_add_f32_e32 v11, v12, v13
	v_add_f32_e32 v12, v10, v11
	v_lshlrev_b64 v[10:11], 13, v[134:135]
	v_lshl_add_u64 v[10:11], v[126:127], 0, v[10:11]
	global_store_dword v[10:11], v12, off
	ds_read_b128 v[106:109], v228 offset:61440
	ds_read_b128 v[110:113], v229 offset:61440
	ds_read_b128 v[10:13], v230 offset:61440
	ds_read_b128 v[14:17], v231 offset:61440
	s_mov_b64 s[40:41], -1
	s_and_b64 vcc, exec, s[4:5]
	s_cbranch_vccnz .LBB0_744
	v_lshl_add_u32 v114, v114, 4, v117
	v_sub_u32_e32 v134, 0x1fff, v114
	s_mov_b64 s[40:41], 0

.LBB0_764:
	s_or_b64 exec, exec, s[40:41]
	ds_read_b128 v[106:109], v224 offset:45056
	ds_read_b128 v[110:113], v225 offset:45056
	ds_read_b128 v[18:21], v226 offset:45056
	ds_read_b128 v[22:25], v227 offset:45056
	s_mov_b64 s[40:41], -1
	s_and_b64 vcc, exec, s[4:5]
	v_lshl_add_u32 v188, s46, 4, v125
	s_cbranch_vccnz .LBB0_766
	v_sub_u32_e32 v132, 0x1fff, v188
	s_mov_b64 s[40:41], 0

.LBB0_768:
	s_waitcnt lgkmcnt(2)
	v_pk_add_f32 v[108:109], v[108:109], v[112:113]
	v_pk_add_f32 v[106:107], v[106:107], v[110:111]
	s_waitcnt lgkmcnt(0)
	v_pk_add_f32 v[20:21], v[20:21], v[24:25]
	v_pk_add_f32 v[18:19], v[18:19], v[22:23]
	v_pk_add_f32 v[20:21], v[108:109], v[20:21]
	v_pk_add_f32 v[18:19], v[106:107], v[18:19]
	v_ashrrev_i32_e32 v133, 31, v132
	v_add_f32_e32 v18, v18, v19
	v_add_f32_e32 v19, v20, v21
	v_add_f32_e32 v114, v18, v19
	v_lshlrev_b64 v[18:19], 13, v[132:133]
	v_lshl_add_u64 v[132:133], v[126:127], 0, v[18:19]
	ds_read_b128 v[106:109], v224 offset:61440
	ds_read_b128 v[110:113], v225 offset:61440
	ds_read_b128 v[18:21], v226 offset:61440
	ds_read_b128 v[22:25], v227 offset:61440
	s_mov_b64 s[40:41], -1
	s_and_b64 vcc, exec, s[4:5]
	v_lshl_add_u32 v187, s46, 4, v117
	global_store_dword v[132:133], v114, off
	s_cbranch_vccnz .LBB0_770
	v_sub_u32_e32 v132, 0x1fff, v187
	s_mov_b64 s[40:41], 0

.LBB0_790:
	s_or_b64 exec, exec, s[52:53]
	ds_read_b128 v[106:109], v228 offset:45056
	ds_read_b128 v[110:113], v229 offset:45056
	ds_read_b128 v[90:93], v230 offset:45056
	ds_read_b128 v[94:97], v231 offset:45056
	s_and_b64 vcc, exec, s[4:5]
	s_mov_b64 s[52:53], -1
	s_cbranch_vccnz .LBB0_792
	s_waitcnt vmcnt(22)
	v_sub_u32_e32 v148, 0x1fef, v188
	s_mov_b64 s[52:53], 0

.LBB0_794:
	s_waitcnt lgkmcnt(2)
	v_pk_add_f32 v[108:109], v[108:109], v[112:113]
	v_pk_add_f32 v[106:107], v[106:107], v[110:111]
	s_waitcnt lgkmcnt(0)
	v_pk_add_f32 v[92:93], v[92:93], v[96:97]
	v_pk_add_f32 v[90:91], v[90:91], v[94:95]
	v_pk_add_f32 v[92:93], v[108:109], v[92:93]
	v_pk_add_f32 v[90:91], v[106:107], v[90:91]
	s_waitcnt vmcnt(22)
	v_ashrrev_i32_e32 v149, 31, v148
	v_add_f32_e32 v90, v90, v91
	v_add_f32_e32 v91, v92, v93
	v_add_f32_e32 v92, v90, v91
	v_lshlrev_b64 v[90:91], 13, v[148:149]
	v_lshl_add_u64 v[90:91], v[126:127], 0, v[90:91]
	global_store_dword v[90:91], v92, off
	ds_read_b128 v[106:109], v228 offset:61440
	ds_read_b128 v[110:113], v229 offset:61440
	ds_read_b128 v[90:93], v230 offset:61440
	ds_read_b128 v[94:97], v231 offset:61440
	s_mov_b64 s[52:53], -1
	s_and_b64 vcc, exec, s[4:5]
	s_cbranch_vccnz .LBB0_796
	v_sub_u32_e32 v148, 0x1fef, v187
	s_mov_b64 s[52:53], 0

.LBB0_817:
	s_or_b64 exec, exec, s[42:43]
	ds_read_b128 v[106:109], v224 offset:45056
	ds_read_b128 v[110:113], v225 offset:45056
	ds_read_b128 v[98:101], v226 offset:45056
	ds_read_b128 v[102:105], v227 offset:45056
	s_and_b64 vcc, exec, s[4:5]
	s_mov_b64 s[42:43], -1
	s_cbranch_vccnz .LBB0_819
	v_sub_u32_e32 v156, 0x1fdf, v188
	s_mov_b64 s[42:43], 0

.LBB0_821:
	s_waitcnt lgkmcnt(2)
	v_pk_add_f32 v[108:109], v[108:109], v[112:113]
	v_pk_add_f32 v[106:107], v[106:107], v[110:111]
	s_waitcnt lgkmcnt(0)
	v_pk_add_f32 v[100:101], v[100:101], v[104:105]
	v_pk_add_f32 v[98:99], v[98:99], v[102:103]
	v_pk_add_f32 v[100:101], v[108:109], v[100:101]
	v_pk_add_f32 v[98:99], v[106:107], v[98:99]
	v_ashrrev_i32_e32 v157, 31, v156
	v_add_f32_e32 v98, v98, v99
	v_add_f32_e32 v99, v100, v101
	v_add_f32_e32 v100, v98, v99
	v_lshlrev_b64 v[98:99], 13, v[156:157]
	v_lshl_add_u64 v[98:99], v[126:127], 0, v[98:99]
	global_store_dword v[98:99], v100, off
	ds_read_b128 v[106:109], v224 offset:61440
	ds_read_b128 v[110:113], v225 offset:61440
	ds_read_b128 v[98:101], v226 offset:61440
	ds_read_b128 v[102:105], v227 offset:61440
	s_mov_b64 s[42:43], -1
	s_and_b64 vcc, exec, s[4:5]
	s_cbranch_vccnz .LBB0_823
	v_sub_u32_e32 v156, 0x1fdf, v187
	s_mov_b64 s[42:43], 0
